# D1+A2 plus C1: conflict-free 16-row XOR swizzle of the K tile image (DMA source mapping + QK read addresses)
# speedup vs baseline: 1.0026x; 1.0026x over previous
; __device__ __forceinline__ int ltid() { int t = threadIdx.x; asm volatile("" : "+v"(t)); return t; }
; __device__ __forceinline__ int v_st(int k, int c) { const int kk = (k & ~0xC) | ((k & 4) << 1) | ((k & 8) >> 1); return ((kk >> 3) * 4 + (c >> 5)) * 512 + ((kk & 7) * 32 + (c & 31)) * 2; }
; #define A2_LOADT(t) do { const size_t ro_ = (size_t)((t) * 64 + sr) * D + sc; \
;         sk0 = att::load8(c.K + ro_); sk1 = att::load8(c.K + ro_ + 32 * D); sv00 = att::load8(c.V0 + ro_); sv01 = att::load8(c.V0 + ro_ + 32 * D); sv10 = att::load8(c.V1 + ro_); sv11 = att::load8(c.V1 + ro_ + 32 * D); } while (0)
; __device__ __forceinline__ void attn2_block(const Blk& c, char* lds) {
;     const int tid = ltid(), wid = __builtin_amdgcn_readfirstlane(tid >> 6), lane = tid & 63, r32 = lane & 31, hi = lane >> 5;
;     const int g = wid & 3;
;     const int NT = (c.P0 + 127) / 64 + 1;
;     const int sr = tid >> 4, sc = (tid & 15) * 8, kws = KSWZ(sr, sc * 2), vst0 = att::v_st(sr, sc), vst1 = att::v_st(32 + sr, sc);
;     bf16x8 sk0, sk1, sv00, sv01, sv10, sv11;
;     float* ALb = (float*)(lds + L_AL) + g * 64; unsigned* FLb = (unsigned*)(lds + L_FL) + g * 2; float* LBb = (float*)(lds + L_LB) + g * 32;
;     char* Pb = lds + L_P + g * 8192;
;     A2_LOADT(0);
.LBB0_540:
	v_mov_b32_e32 v2, v1
	s_and_b64 s[2:3], s[72:73], exec
	v_ashrrev_i32_e32 v210, 4, v2
	v_lshlrev_b32_e32 v10, 3, v2
	v_and_b32_e32 v222, 0x78, v10
	v_ashrrev_i32_e32 v211, 31, v210
	v_lshlrev_b32_e32 v11, 1, v222
	v_lshlrev_b64 v[212:213], 8, v[210:211]
	v_or_b32_e32 v4, v212, v11
	v_mov_b32_e32 v5, v213
	v_readfirstlane_b32 s2, v2
	v_and_b32_e32 v8, 3, v210
	v_lshlrev_b32_e32 v4, 8, v210
	v_and_b32_e32 v5, 0x70, v2
	v_bitop3_b32 v4, v11, v4, v5 bitop3:0xde
	v_and_b32_e32 v5, 0xfffff0, v210
	v_lshlrev_b32_e32 v6, 1, v210
	v_and_or_b32 v5, v6, 8, v5
	v_lshrrev_b32_e32 v6, 1, v210
	v_lshrrev_b32_e32 v5, 1, v5
	v_bfe_u32 v7, v10, 5, 2
	v_or_b32_e32 v5, v5, v7
	v_and_or_b32 v6, v6, 4, v8
	s_cselect_b32 s30, s52, s53
	s_ashr_i32 s2, s2, 6
	v_lshlrev_b32_e32 v5, 9, v5
	v_lshlrev_b32_e32 v6, 6, v6
	v_and_b32_e32 v8, 48, v11
	s_and_b32 s82, s2, 3
	v_or3_b32 v223, v5, v6, v8
	v_add_u32_e32 v5, 32, v210
	v_and_b32_e32 v9, 0xfffff0, v5
	v_lshlrev_b32_e32 v5, 1, v5
	s_lshl_b32 s3, s82, 8
	v_and_or_b32 v5, v5, 8, v9
	s_add_i32 s17, s3, 0
	s_lshl_b32 s3, s82, 3
	v_lshrrev_b32_e32 v5, 1, v5
	s_add_i32 s79, s3, 0
	s_lshl_b32 s3, s82, 7
	v_or_b32_e32 v5, v5, v7
	s_add_i32 s65, s3, 0
	s_lshl_b32 s3, s82, 13
	v_lshlrev_b32_e32 v5, 9, v5
	s_add_i32 s16, s3, 0
	v_and_b32_e32 v225, 63, v2
	v_and_b32_e32 v211, 31, v2
	v_bfe_u32 v226, v2, 5, 1
	s_lshr_b32 s78, s30, 6
	v_or3_b32 v224, v5, v6, v8
	s_add_i32 s17, s17, 0x20000
	s_add_i32 s79, s79, 0x20400
	s_add_i32 s65, s65, 0x20480
	s_add_i32 s16, s16, 0x18000
	v_and_b32_e32 v2, 15, v2
	v_lshlrev_b32_e32 v216, 4, v226
	v_add_u32_e32 v229, 0, v4
	v_add_u32_e32 v227, 0, v223
	v_add_u32_e32 v228, 0, v224
	v_lshl_or_b32 v214, v2, 4, v212
	s_lshl_b32 s100, s2, 11
	v_lshrrev_b32_e32 v4, 6, v1
	v_bfe_u32 v5, v1, 4, 2
	v_lshl_or_b32 v4, v4, 3, v5
	v_and_b32_e32 v6, 15, v1
	v_bfe_u32 v7, v1, 6, 1
	v_lshl_or_b32 v7, v7, 3, v5
	v_xor_b32_e32 v6, v6, v7
	v_lshlrev_b32_e32 v6, 4, v6
	v_lshl_or_b32 v4, v4, 8, v6
	v_mov_b32_e32 v5, 0
	v_xor_b32_e32 v6, 64, v4
	v_mov_b32_e32 v7, 0
	v_lshl_add_u64 v[164:165], s[0:1], 0, v[4:5]
	v_lshl_add_u64 v[166:167], s[0:1], 0, v[6:7]
	v_bfe_u32 v4, v1, 7, 2
	v_bfe_u32 v6, v1, 4, 1
	v_lshl_or_b32 v4, v4, 1, v6
	v_bfe_u32 v6, v1, 6, 1
	v_lshl_or_b32 v4, v4, 1, v6
	v_bfe_u32 v6, v1, 2, 2
	v_lshl_or_b32 v4, v4, 2, v6
	v_bfe_u32 v6, v1, 5, 1
	v_and_b32_e32 v8, 3, v1
	v_lshl_or_b32 v6, v6, 2, v8
	v_lshlrev_b32_e32 v6, 4, v6
	v_lshl_or_b32 v4, v4, 8, v6
	v_lshl_add_u64 v[168:169], s[6:7], 0, v[4:5]
	v_lshl_add_u64 v[170:171], s[8:9], 0, v[4:5]
	s_add_i32 m0, s100, 0x10000
	s_mov_b64 s[10:11], 0x4000
	global_load_lds_dwordx4 v[164:165], off
	global_load_lds_dwordx4 v[166:167], off offset:1024
	v_lshl_add_u64 v[164:165], v[164:165], 0, s[10:11]
	v_lshl_add_u64 v[166:167], v[166:167], 0, s[10:11]
	s_cmp_gt_i32 s2, 3
	s_mov_b64 s[2:3], -1
	s_cbranch_scc1 .LBB0_542
	s_and_b64 vcc, exec, s[2:3]
	s_cbranch_vccz .LBB0_539
	s_branch .LBB0_551

; #define SBAR() __builtin_amdgcn_sched_barrier(0)
; #define A2_LOADT(t) do { const size_t ro_ = (size_t)((t) * 64 + sr) * D + sc; \
;         sk0 = att::load8(c.K + ro_); sk1 = att::load8(c.K + ro_ + 32 * D); sv00 = att::load8(c.V0 + ro_); sv01 = att::load8(c.V0 + ro_ + 32 * D); sv10 = att::load8(c.V1 + ro_); sv11 = att::load8(c.V1 + ro_ + 32 * D); } while (0)
; #define A2_WRITET(buf) do { char* kd_ = lds + L_K + (buf) * SHM_K; char* vd_ = lds + L_V + (buf) * 2 * SHM_V; \
;         *(bf16x8*)(kd_ + kws) = sk0; *(bf16x8*)(kd_ + kws + 32 * 256) = sk1; *(bf16x8*)(vd_ + vst0) = sv00; *(bf16x8*)(vd_ + vst1) = sv01; *(bf16x8*)(vd_ + SHM_V + vst0) = sv10; *(bf16x8*)(vd_ + SHM_V + vst1) = sv11; } while (0)
; __device__ __forceinline__ void qkt_rt(f32x16& p0, f32x16& p1, const char* Kb, int r32, int hi, const bf16x8* qr) {
;     p0 = f32x16{}; p1 = f32x16{};
;     const char* kb[4];
; #pragma unroll
;     for (int dd = 0; dd < 4; ++dd) kb[dd] = Kb + KSWZ(r32, (dd * 16 + hi * 8) * 2);
; #pragma unroll
;     for (int d0 = 0; d0 < 8; ++d0) { const char* a = kb[d0 & 3] + (d0 >> 2) * 128;
;         bf16x8 b0 = *reinterpret_cast<const bf16x8*>(a);
;         bf16x8 b1 = *reinterpret_cast<const bf16x8*>(a + 32 * 256);
;         p0 = __builtin_amdgcn_mfma_f32_32x32x16_bf16(b0, qr[d0], p0, 0, 0, 0);
;         p1 = __builtin_amdgcn_mfma_f32_32x32x16_bf16(b1, qr[d0], p1, 0, 0, 0); }
; }
; __device__ __forceinline__ void attn2_block(const Blk& c, char* lds) {
;     ...
;     if (wid < 4) {
;         bf16x8 qr[8];
; #pragma unroll
;         for (int d0 = 0; d0 < 8; ++d0) qr[d0] = att::load8(c.Q + (size_t)(g * 32 + r32) * D + d0 * 16 + hi * 8);
;         asm volatile("s_waitcnt vmcnt(0)" ::: "memory"); A2_WRITET(0); __syncthreads();
;         const int qlo = c.P0 + g * 32, qm = qlo + r32 - 4 * hi;
;         const float* bt = (const float*)(lds + L_BT) + c.hm * 256;
;         float m_reg = -1e30f, l_reg = 0.f;
;         for (int s = 0; s <= NT; ++s) {
;             const int par = s & 1;
;             if (s + 1 < NT) A2_LOADT(s + 1);
;             SBAR();
;             if (s < NT) {
;                 f32x16 p0, p1; float mn, al; bf16x8 pa0, pa1, pa2, pa3;
;                 qkt_rt(p0, p1, lds + L_K + par * SHM_K, r32, hi, qr);
;                 const int kb_ = s * 64;
.LBB0_551:
	s_or_b64 s[2:3], s[14:15], s[30:31]
	s_lshl_b32 s10, s82, 5
	s_lshl_b64 s[2:3], s[2:3], 8
	s_add_u32 s2, s27, s2
	v_or_b32_e32 v2, s10, v211
	s_addc_u32 s3, s34, s3
	v_lshlrev_b32_e32 v2, 8, v2
	v_lshl_add_u64 v[4:5], s[2:3], 0, v[2:3]
	v_mov_b32_e32 v217, v3
	v_lshl_add_u64 v[4:5], v[4:5], 0, v[216:217]
	global_load_dwordx4 v[104:107], v[4:5], off
	global_load_dwordx4 v[100:103], v[4:5], off offset:32
	global_load_dwordx4 v[96:99], v[4:5], off offset:64
	global_load_dwordx4 v[92:95], v[4:5], off offset:96
	global_load_dwordx4 v[88:91], v[4:5], off offset:128
	global_load_dwordx4 v[84:87], v[4:5], off offset:160
	global_load_dwordx4 v[80:83], v[4:5], off offset:192
	global_load_dwordx4 v[76:79], v[4:5], off offset:224
	s_or_b32 s85, s10, s30
	s_add_i32 s10, s30, s10
	s_waitcnt vmcnt(0)
	v_lshlrev_b32_e32 v4, 4, v211
	s_movk_i32 s2, 0x70
	s_lshl_b32 s11, s30, 8
	s_sub_i32 s10, s10, 27
	v_and_b32_e32 v5, 0x70, v4
	v_bitop3_b32 v121, v216, v4, s2 bitop3:0x78
	s_movk_i32 s2, 0x60
	v_lshlrev_b32_e32 v114, 2, v226
	s_and_b32 s11, s11, 0x1fc000
	v_add_u32_e32 v4, s10, v211
	v_mov_b32_e32 v215, v213
	v_add_u32_e32 v116, 0x10000, v229
	v_lshl_add_u32 v2, v211, 2, s17
	v_lshlrev_b32_e32 v119, 8, v211
	v_bitop3_b32 v122, v216, v5, 32 bitop3:0x36
	v_bitop3_b32 v123, v216, v5, 64 bitop3:0x36
	v_bitop3_b32 v124, v216, v5, s2 bitop3:0x36
	v_and_b32_e32 v126, 15, v211
	v_lshlrev_b32_e32 v126, 4, v126
	v_xor_b32_e32 v121, v216, v126
	v_xor_b32_e32 v122, 32, v121
	v_xor_b32_e32 v123, 64, v121
	v_xor_b32_e32 v124, 0x60, v121
	v_xor_b32_e32 v126, 0x80, v121
	v_xor_b32_e32 v127, 0x80, v122
	v_xor_b32_e32 v128, 0x80, v123
	v_xor_b32_e32 v129, 0x80, v124
	s_add_i32 s86, s85, 0xffffff80
	v_lshl_add_u32 v112, v225, 4, s16
	v_cmp_gt_u32_e64 s[2:3], 32, v225
	s_mov_b32 s84, 0
	v_cmp_eq_u32_e64 s[4:5], 0, v225
	s_add_u32 s87, s11, 0x4000
	v_sub_u32_e32 v125, v4, v114
	v_lshl_add_u64 v[108:109], s[46:47], 0, v[214:215]
	v_lshl_add_u64 v[110:111], s[58:59], 0, v[214:215]
	v_mov_b32_e32 v117, 0
	v_mov_b32_e32 v113, 0xf149f2ca
	s_mov_b64 s[82:83], 0
	s_mov_b32 s30, 0
	s_waitcnt lgkmcnt(0)
	s_barrier
.LBB0_552:
	s_and_b32 s88, s30, 1
	s_lshl_b32 s10, s88, 15
	s_add_i32 s10, s10, s100
	s_mov_b32 m0, s10
	v_lshl_add_u64 v[52:53], v[168:169], 0, s[82:83]
	global_load_lds_dwordx4 v[52:53], off
	s_add_i32 m0, s10, 0x380
	v_lshl_add_u64 v[54:55], v[170:171], 0, s[82:83]
	global_load_lds_dwordx4 v[52:53], off offset:128
	s_add_i32 m0, s10, 0x4000
	s_nop 0
	global_load_lds_dwordx4 v[54:55], off
	s_add_i32 m0, s10, 0x4380
	s_nop 0
	global_load_lds_dwordx4 v[54:55], off offset:128
	s_xor_b32 s10, s88, 1
	s_lshl_b32 s10, s10, 14
	s_add_i32 s10, s10, s100
	s_add_i32 m0, s10, 0x10000
	v_lshl_add_u64 v[56:57], v[164:165], 0, s[82:83]
	v_lshl_add_u64 v[58:59], v[166:167], 0, s[82:83]
	global_load_lds_dwordx4 v[56:57], off
	global_load_lds_dwordx4 v[58:59], off offset:1024
	s_lshl_b32 s10, s88, 14
	s_add_i32 s10, s10, 0
	s_add_i32 s10, s10, 0x10000
	v_add3_u32 v40, s10, v121, v119
	ds_read_b128 v[4:7], v40
	v_add3_u32 v41, s10, v122, v119
	ds_read_b128 v[36:39], v41
	v_add3_u32 v42, s10, v123, v119
	v_add3_u32 v43, s10, v124, v119
	v_add3_u32 v44, s10, v126, v119
	v_add3_u32 v45, s10, v127, v119
	v_add3_u32 v46, s10, v128, v119
	v_add3_u32 v47, s10, v129, v119
	s_add_i32 s10, s84, 63
	s_cmp_le_i32 s10, s86
	s_waitcnt lgkmcnt(1)
	v_mfma_f32_32x32x16_bf16 v[20:35], v[4:7], v[104:107], 0
	ds_read_b128 v[4:7], v40 offset:8192
	s_waitcnt lgkmcnt(1)
	v_mfma_f32_32x32x16_bf16 v[20:35], v[36:39], v[100:103], v[20:35]
	ds_read_b128 v[36:39], v41 offset:8192
	s_waitcnt lgkmcnt(1)
	v_mfma_f32_32x32x16_bf16 v[4:19], v[4:7], v[104:107], 0
	s_waitcnt lgkmcnt(0)
	v_mfma_f32_32x32x16_bf16 v[4:19], v[36:39], v[100:103], v[4:19]
	ds_read_b128 v[36:39], v42
	s_waitcnt lgkmcnt(0)
	v_mfma_f32_32x32x16_bf16 v[20:35], v[36:39], v[96:99], v[20:35]
	ds_read_b128 v[36:39], v42 offset:8192
	s_waitcnt lgkmcnt(0)
	v_mfma_f32_32x32x16_bf16 v[4:19], v[36:39], v[96:99], v[4:19]
	ds_read_b128 v[36:39], v43
	s_waitcnt lgkmcnt(0)
	v_mfma_f32_32x32x16_bf16 v[20:35], v[36:39], v[92:95], v[20:35]
	ds_read_b128 v[36:39], v43 offset:8192
	s_waitcnt lgkmcnt(0)
	v_mfma_f32_32x32x16_bf16 v[4:19], v[36:39], v[92:95], v[4:19]
	ds_read_b128 v[36:39], v44
	s_waitcnt lgkmcnt(0)
	v_mfma_f32_32x32x16_bf16 v[20:35], v[36:39], v[88:91], v[20:35]
	ds_read_b128 v[36:39], v44 offset:8192
	s_waitcnt lgkmcnt(0)
	v_mfma_f32_32x32x16_bf16 v[4:19], v[36:39], v[88:91], v[4:19]
	ds_read_b128 v[36:39], v45
	s_waitcnt lgkmcnt(0)
	v_mfma_f32_32x32x16_bf16 v[20:35], v[36:39], v[84:87], v[20:35]
	ds_read_b128 v[36:39], v45 offset:8192
	s_waitcnt lgkmcnt(0)
	v_mfma_f32_32x32x16_bf16 v[4:19], v[36:39], v[84:87], v[4:19]
	ds_read_b128 v[36:39], v46
	s_waitcnt lgkmcnt(0)
	v_mfma_f32_32x32x16_bf16 v[20:35], v[36:39], v[80:83], v[20:35]
	ds_read_b128 v[36:39], v46 offset:8192
	s_waitcnt lgkmcnt(0)
	v_mfma_f32_32x32x16_bf16 v[4:19], v[36:39], v[80:83], v[4:19]
	ds_read_b128 v[36:39], v47
	s_waitcnt lgkmcnt(0)
	v_mfma_f32_32x32x16_bf16 v[20:35], v[36:39], v[76:79], v[20:35]
	ds_read_b128 v[36:39], v47 offset:8192
	s_waitcnt lgkmcnt(0)
	v_mfma_f32_32x32x16_bf16 v[4:19], v[36:39], v[76:79], v[4:19]
	s_cbranch_scc1 .LBB0_586
; __device__ __forceinline__ void bias_mask_tile(f32x16& p0, f32x16& p1, int dq, const float* bt) {
;     const float NEG = -__builtin_inff();
; #pragma unroll
;     for (int r = 0; r < 16; ++r) {
;         const int c = (r & 3) + 8 * (r >> 2);
;         const int d0 = dq - c, d1 = dq - c - 32;
;         const unsigned i0 = (unsigned)d0 < 255u ? (unsigned)d0 : 255u, i1 = (unsigned)d1 < 255u ? (unsigned)d1 : 255u;
;         const float b0 = bt[i0], b1 = bt[i1];
;         p0[r] = d0 >= 0 ? p0[r] + b0 : NEG;
;         p1[r] = d1 >= 0 ? p1[r] + b1 : NEG;
;     }
; }
	v_add_u32_e32 v115, 27, v125
	v_lshl_add_u32 v36, v115, 2, s64
	v_add_u32_e32 v36, 0xffffff14, v36
	ds_read_b32 v132, v36 offset:236
	ds_read_b32 v133, v36 offset:232
	ds_read_b32 v134, v36 offset:228
	ds_read_b32 v135, v36 offset:224
	ds_read_b32 v136, v36 offset:204
	ds_read_b32 v137, v36 offset:200
	ds_read_b32 v138, v36 offset:196
	ds_read_b32 v139, v36 offset:192
	ds_read_b32 v140, v36 offset:172
	ds_read_b32 v141, v36 offset:168
	ds_read_b32 v142, v36 offset:164
	ds_read_b32 v143, v36 offset:160
	ds_read_b32 v144, v36 offset:140
	ds_read_b32 v145, v36 offset:136
	ds_read_b32 v146, v36 offset:132
	v_cmp_lt_i32_e32 vcc, -1, v115
	v_cmp_lt_i32_e64 s[16:17], 0, v115
	s_waitcnt lgkmcnt(14)
	v_add_f32_e32 v20, v20, v132
	ds_read_b32 v147, v36 offset:128
	s_waitcnt lgkmcnt(14)
	v_add_f32_e32 v21, v21, v133
	ds_read_b32 v148, v36 offset:108
	v_cndmask_b32_e32 v20, v240, v20, vcc
	v_cndmask_b32_e64 v21, v240, v21, s[16:17]
	v_cmp_lt_i32_e32 vcc, 1, v115
	v_cmp_lt_i32_e64 s[16:17], 2, v115
	s_waitcnt lgkmcnt(14)
	v_add_f32_e32 v22, v22, v134
	ds_read_b32 v149, v36 offset:104
	s_waitcnt lgkmcnt(14)
	v_add_f32_e32 v23, v23, v135
	ds_read_b32 v150, v36 offset:100
	v_cndmask_b32_e32 v22, v240, v22, vcc
	v_cndmask_b32_e64 v23, v240, v23, s[16:17]
	v_cmp_lt_i32_e32 vcc, 7, v115
	v_cmp_lt_i32_e64 s[16:17], 8, v115
	s_waitcnt lgkmcnt(14)
	v_add_f32_e32 v24, v24, v136
	ds_read_b32 v151, v36 offset:96
	s_waitcnt lgkmcnt(14)
	v_add_f32_e32 v25, v25, v137
	ds_read_b32 v152, v36 offset:76
	v_cndmask_b32_e32 v24, v240, v24, vcc
	v_cndmask_b32_e64 v25, v240, v25, s[16:17]
	v_cmp_lt_i32_e32 vcc, 9, v115
	v_cmp_lt_i32_e64 s[16:17], 10, v115
	s_waitcnt lgkmcnt(14)
	v_add_f32_e32 v26, v26, v138
	ds_read_b32 v153, v36 offset:72
	s_waitcnt lgkmcnt(14)
	v_add_f32_e32 v27, v27, v139
	ds_read_b32 v154, v36 offset:68
	v_cndmask_b32_e32 v26, v240, v26, vcc
	v_cndmask_b32_e64 v27, v240, v27, s[16:17]
	v_cmp_lt_i32_e32 vcc, 15, v115
	v_cmp_lt_i32_e64 s[16:17], 16, v115
	s_waitcnt lgkmcnt(14)
	v_add_f32_e32 v28, v28, v140
	ds_read_b32 v155, v36 offset:64
	s_waitcnt lgkmcnt(14)
	v_add_f32_e32 v29, v29, v141
	ds_read_b32 v60, v36 offset:44
	v_cndmask_b32_e32 v28, v240, v28, vcc
	v_cndmask_b32_e64 v29, v240, v29, s[16:17]
	v_cmp_lt_i32_e32 vcc, 17, v115
	v_cmp_lt_i32_e64 s[16:17], 18, v115
	s_waitcnt lgkmcnt(14)
	v_add_f32_e32 v30, v30, v142
	ds_read_b32 v61, v36 offset:40
	s_waitcnt lgkmcnt(14)
	v_add_f32_e32 v31, v31, v143
	ds_read_b32 v62, v36 offset:36
	v_cndmask_b32_e32 v30, v240, v30, vcc
	v_cndmask_b32_e64 v31, v240, v31, s[16:17]
	v_cmp_lt_i32_e32 vcc, 23, v115
	v_cmp_lt_i32_e64 s[16:17], 24, v115
	s_waitcnt lgkmcnt(14)
	v_add_f32_e32 v32, v32, v144
	ds_read_b32 v63, v36 offset:32
	s_waitcnt lgkmcnt(14)
	v_add_f32_e32 v33, v33, v145
	ds_read_b32 v64, v36 offset:12
	v_cndmask_b32_e32 v32, v240, v32, vcc
	v_cndmask_b32_e64 v33, v240, v33, s[16:17]
	v_cmp_lt_i32_e32 vcc, 25, v115
	v_cmp_lt_i32_e64 s[16:17], 26, v115
	s_waitcnt lgkmcnt(14)
	v_add_f32_e32 v34, v34, v146
	ds_read_b32 v65, v36 offset:8
	s_waitcnt lgkmcnt(14)
	v_add_f32_e32 v35, v35, v147
	ds_read_b32 v66, v36 offset:4
	v_cndmask_b32_e32 v34, v240, v34, vcc
	v_cndmask_b32_e64 v35, v240, v35, s[16:17]
	v_cmp_lt_i32_e32 vcc, 31, v115
	v_cmp_lt_i32_e64 s[16:17], 32, v115
	s_waitcnt lgkmcnt(14)
	v_add_f32_e32 v4, v4, v148
	ds_read_b32 v67, v36 offset:0
	s_waitcnt lgkmcnt(14)
	v_add_f32_e32 v5, v5, v149
	v_cndmask_b32_e32 v4, v240, v4, vcc
	v_cndmask_b32_e64 v5, v240, v5, s[16:17]
	v_cmp_lt_i32_e32 vcc, 33, v115
	v_cmp_lt_i32_e64 s[16:17], 34, v115
	s_waitcnt lgkmcnt(13)
	v_add_f32_e32 v6, v6, v150
	s_waitcnt lgkmcnt(12)
	v_add_f32_e32 v7, v7, v151
	v_cndmask_b32_e32 v6, v240, v6, vcc
	v_cndmask_b32_e64 v7, v240, v7, s[16:17]
	v_cmp_lt_i32_e32 vcc, 39, v115
	v_cmp_lt_i32_e64 s[16:17], 40, v115
	s_waitcnt lgkmcnt(11)
	v_add_f32_e32 v8, v8, v152
	s_waitcnt lgkmcnt(10)
	v_add_f32_e32 v9, v9, v153
	v_cndmask_b32_e32 v8, v240, v8, vcc
	v_cndmask_b32_e64 v9, v240, v9, s[16:17]
	v_cmp_lt_i32_e32 vcc, 41, v115
	v_cmp_lt_i32_e64 s[16:17], 42, v115
	s_waitcnt lgkmcnt(9)
	v_add_f32_e32 v10, v10, v154
	s_waitcnt lgkmcnt(8)
	v_add_f32_e32 v11, v11, v155
	v_cndmask_b32_e32 v10, v240, v10, vcc
	v_cndmask_b32_e64 v11, v240, v11, s[16:17]
	v_cmp_lt_i32_e32 vcc, 47, v115
	v_cmp_lt_i32_e64 s[16:17], 48, v115
	s_waitcnt lgkmcnt(7)
	v_add_f32_e32 v12, v12, v60
	s_waitcnt lgkmcnt(6)
	v_add_f32_e32 v13, v13, v61
	v_cndmask_b32_e32 v12, v240, v12, vcc
	v_cndmask_b32_e64 v13, v240, v13, s[16:17]
	v_cmp_lt_i32_e32 vcc, 49, v115
	v_cmp_lt_i32_e64 s[16:17], 50, v115
	s_waitcnt lgkmcnt(5)
	v_add_f32_e32 v14, v14, v62
	s_waitcnt lgkmcnt(4)
	v_add_f32_e32 v15, v15, v63
	v_cndmask_b32_e32 v14, v240, v14, vcc
	v_cndmask_b32_e64 v15, v240, v15, s[16:17]
	v_cmp_lt_i32_e32 vcc, 55, v115
	v_cmp_lt_i32_e64 s[16:17], 56, v115
	s_waitcnt lgkmcnt(3)
	v_add_f32_e32 v16, v16, v64
	s_waitcnt lgkmcnt(2)
	v_add_f32_e32 v17, v17, v65
	v_cndmask_b32_e32 v16, v240, v16, vcc
	v_cndmask_b32_e64 v17, v240, v17, s[16:17]
	v_cmp_lt_i32_e32 vcc, 57, v115
	v_cmp_lt_i32_e64 s[16:17], 58, v115
	s_waitcnt lgkmcnt(1)
	v_add_f32_e32 v18, v18, v66
	s_waitcnt lgkmcnt(0)
	v_add_f32_e32 v19, v19, v67
	v_cndmask_b32_e32 v18, v240, v18, vcc
	v_cndmask_b32_e64 v19, v240, v19, s[16:17]

; #define SBAR() __builtin_amdgcn_sched_barrier(0)
; #define A2_LOADT(t) do { const size_t ro_ = (size_t)((t) * 64 + sr) * D + sc; \
;         sk0 = att::load8(c.K + ro_); sk1 = att::load8(c.K + ro_ + 32 * D); sv00 = att::load8(c.V0 + ro_); sv01 = att::load8(c.V0 + ro_ + 32 * D); sv10 = att::load8(c.V1 + ro_); sv11 = att::load8(c.V1 + ro_ + 32 * D); } while (0)
; __device__ __forceinline__ void qkt_rt(f32x16& p0, f32x16& p1, const char* Kb, int r32, int hi, const bf16x8* qr) {
;     p0 = f32x16{}; p1 = f32x16{};
;     const char* kb[4];
; #pragma unroll
;     for (int dd = 0; dd < 4; ++dd) kb[dd] = Kb + KSWZ(r32, (dd * 16 + hi * 8) * 2);
; #pragma unroll
;     for (int d0 = 0; d0 < 8; ++d0) { const char* a = kb[d0 & 3] + (d0 >> 2) * 128;
;         bf16x8 b0 = *reinterpret_cast<const bf16x8*>(a);
;         bf16x8 b1 = *reinterpret_cast<const bf16x8*>(a + 32 * 256);
;         p0 = __builtin_amdgcn_mfma_f32_32x32x16_bf16(b0, qr[d0], p0, 0, 0, 0);
;         p1 = __builtin_amdgcn_mfma_f32_32x32x16_bf16(b1, qr[d0], p1, 0, 0, 0); }
; }
; __device__ __forceinline__ void attn2_block(const Blk& c, char* lds) {
;     ...
;             if (s + 1 < NT) A2_LOADT(s + 1);
;             SBAR();
;             if (s < NT) {
;                 f32x16 p0, p1; float mn, al; bf16x8 pa0, pa1, pa2, pa3;
;                 qkt_rt(p0, p1, lds + L_K + par * SHM_K, r32, hi, qr);
;                 const int kb_ = s * 64;
;                 if (kb_ + 63 > qlo - 128) att::bias_mask_tile(p0, p1, qm - kb_, bt);
.LBB0_592:
	s_lshl_b32 s10, s88, 15
	s_add_i32 s10, s10, s100
	s_mov_b32 m0, s10
	v_lshl_add_u64 v[52:53], v[168:169], 0, s[82:83]
	global_load_lds_dwordx4 v[52:53], off
	s_add_i32 m0, s10, 0x380
	v_lshl_add_u64 v[54:55], v[170:171], 0, s[82:83]
	global_load_lds_dwordx4 v[52:53], off offset:128
	s_add_i32 m0, s10, 0x4000
	s_nop 0
	global_load_lds_dwordx4 v[54:55], off
	s_add_i32 m0, s10, 0x4380
	s_nop 0
	global_load_lds_dwordx4 v[54:55], off offset:128
	s_add_i32 s10, s16, 0
	s_add_i32 s10, s10, 0x10000
	v_add3_u32 v44, s10, v121, v119
	ds_read_b128 v[4:7], v44
	ds_read_b128 v[8:11], v44 offset:8192
	v_add3_u32 v45, s10, v122, v119
	ds_read_b128 v[36:39], v45
	ds_read_b128 v[40:43], v45 offset:8192
	v_add3_u32 v46, s10, v123, v119
	s_waitcnt lgkmcnt(3)
	v_mfma_f32_32x32x16_bf16 v[20:35], v[4:7], v[104:107], 0
	v_add3_u32 v47, s10, v124, v119
	v_add3_u32 v48, s10, v126, v119
	v_add3_u32 v49, s10, v127, v119
	v_add3_u32 v50, s10, v128, v119
	v_add3_u32 v51, s10, v129, v119
	s_or_b32 s10, s84, 63
	s_cmp_le_i32 s10, s86
	s_waitcnt lgkmcnt(2)
	v_mfma_f32_32x32x16_bf16 v[4:19], v[8:11], v[104:107], 0
	s_waitcnt lgkmcnt(1)
	v_mfma_f32_32x32x16_bf16 v[20:35], v[36:39], v[100:103], v[20:35]
	s_waitcnt lgkmcnt(0)
	v_mfma_f32_32x32x16_bf16 v[4:19], v[40:43], v[100:103], v[4:19]
	ds_read_b128 v[36:39], v46
	ds_read_b128 v[40:43], v46 offset:8192
	s_waitcnt lgkmcnt(1)
	v_mfma_f32_32x32x16_bf16 v[20:35], v[36:39], v[96:99], v[20:35]
	s_waitcnt lgkmcnt(0)
	v_mfma_f32_32x32x16_bf16 v[4:19], v[40:43], v[96:99], v[4:19]
	ds_read_b128 v[36:39], v47
	ds_read_b128 v[40:43], v47 offset:8192
	s_waitcnt lgkmcnt(1)
	v_mfma_f32_32x32x16_bf16 v[20:35], v[36:39], v[92:95], v[20:35]
	s_waitcnt lgkmcnt(0)
	v_mfma_f32_32x32x16_bf16 v[4:19], v[40:43], v[92:95], v[4:19]
	ds_read_b128 v[36:39], v48
	ds_read_b128 v[40:43], v48 offset:8192
	s_waitcnt lgkmcnt(1)
	v_mfma_f32_32x32x16_bf16 v[20:35], v[36:39], v[88:91], v[20:35]
	s_waitcnt lgkmcnt(0)
	v_mfma_f32_32x32x16_bf16 v[4:19], v[40:43], v[88:91], v[4:19]
	ds_read_b128 v[36:39], v49
	ds_read_b128 v[40:43], v49 offset:8192
	s_waitcnt lgkmcnt(1)
	v_mfma_f32_32x32x16_bf16 v[20:35], v[36:39], v[84:87], v[20:35]
	s_waitcnt lgkmcnt(0)
	v_mfma_f32_32x32x16_bf16 v[4:19], v[40:43], v[84:87], v[4:19]
	ds_read_b128 v[36:39], v50
	ds_read_b128 v[40:43], v50 offset:8192
	s_waitcnt lgkmcnt(1)
	v_mfma_f32_32x32x16_bf16 v[20:35], v[36:39], v[80:83], v[20:35]
	s_waitcnt lgkmcnt(0)
	v_mfma_f32_32x32x16_bf16 v[4:19], v[40:43], v[80:83], v[4:19]
	ds_read_b128 v[36:39], v51
	ds_read_b128 v[40:43], v51 offset:8192
	s_waitcnt lgkmcnt(1)
	v_mfma_f32_32x32x16_bf16 v[20:35], v[36:39], v[76:79], v[20:35]
	s_waitcnt lgkmcnt(0)
	v_mfma_f32_32x32x16_bf16 v[4:19], v[40:43], v[76:79], v[4:19]
	s_cbranch_scc1 .LBB0_626
; __device__ __forceinline__ void bias_mask_tile(f32x16& p0, f32x16& p1, int dq, const float* bt) {
;     const float NEG = -__builtin_inff();
; #pragma unroll
;     for (int r = 0; r < 16; ++r) {
;         const int c = (r & 3) + 8 * (r >> 2);
;         const int d0 = dq - c, d1 = dq - c - 32;
;         const unsigned i0 = (unsigned)d0 < 255u ? (unsigned)d0 : 255u, i1 = (unsigned)d1 < 255u ? (unsigned)d1 : 255u;
;         const float b0 = bt[i0], b1 = bt[i1];
;         p0[r] = d0 >= 0 ? p0[r] + b0 : NEG;
;         p1[r] = d1 >= 0 ? p1[r] + b1 : NEG;
;     }
; }
	v_or_b32_e32 v36, s85, v211
	v_or_b32_e32 v37, s84, v114
	v_sub_u32_e32 v76, v36, v37
	v_lshl_add_u32 v36, v76, 2, s64
	v_add_u32_e32 v36, 0xffffff14, v36
	ds_read_b32 v132, v36 offset:236
	ds_read_b32 v133, v36 offset:232
	ds_read_b32 v134, v36 offset:228
	ds_read_b32 v135, v36 offset:224
	ds_read_b32 v136, v36 offset:204
	ds_read_b32 v137, v36 offset:200
	ds_read_b32 v138, v36 offset:196
	ds_read_b32 v139, v36 offset:192
	ds_read_b32 v140, v36 offset:172
	ds_read_b32 v141, v36 offset:168
	ds_read_b32 v142, v36 offset:164
	ds_read_b32 v143, v36 offset:160
	ds_read_b32 v144, v36 offset:140
	ds_read_b32 v145, v36 offset:136
	ds_read_b32 v146, v36 offset:132
	v_cmp_lt_i32_e32 vcc, -1, v76
	v_cmp_lt_i32_e64 s[16:17], 0, v76
	s_waitcnt lgkmcnt(14)
	v_add_f32_e32 v20, v20, v132
	ds_read_b32 v147, v36 offset:128
	s_waitcnt lgkmcnt(14)
	v_add_f32_e32 v21, v21, v133
	ds_read_b32 v148, v36 offset:108
	v_cndmask_b32_e32 v20, v240, v20, vcc
	v_cndmask_b32_e64 v21, v240, v21, s[16:17]
	v_cmp_lt_i32_e32 vcc, 1, v76
	v_cmp_lt_i32_e64 s[16:17], 2, v76
	s_waitcnt lgkmcnt(14)
	v_add_f32_e32 v22, v22, v134
	ds_read_b32 v149, v36 offset:104
	s_waitcnt lgkmcnt(14)
	v_add_f32_e32 v23, v23, v135
	ds_read_b32 v150, v36 offset:100
	v_cndmask_b32_e32 v22, v240, v22, vcc
	v_cndmask_b32_e64 v23, v240, v23, s[16:17]
	v_cmp_lt_i32_e32 vcc, 7, v76
	v_cmp_lt_i32_e64 s[16:17], 8, v76
	s_waitcnt lgkmcnt(14)
	v_add_f32_e32 v24, v24, v136
	ds_read_b32 v151, v36 offset:96
	s_waitcnt lgkmcnt(14)
	v_add_f32_e32 v25, v25, v137
	ds_read_b32 v152, v36 offset:76
	v_cndmask_b32_e32 v24, v240, v24, vcc
	v_cndmask_b32_e64 v25, v240, v25, s[16:17]
	v_cmp_lt_i32_e32 vcc, 9, v76
	v_cmp_lt_i32_e64 s[16:17], 10, v76
	s_waitcnt lgkmcnt(14)
	v_add_f32_e32 v26, v26, v138
	ds_read_b32 v153, v36 offset:72
	s_waitcnt lgkmcnt(14)
	v_add_f32_e32 v27, v27, v139
	ds_read_b32 v154, v36 offset:68
	v_cndmask_b32_e32 v26, v240, v26, vcc
	v_cndmask_b32_e64 v27, v240, v27, s[16:17]
	v_cmp_lt_i32_e32 vcc, 15, v76
	v_cmp_lt_i32_e64 s[16:17], 16, v76
	s_waitcnt lgkmcnt(14)
	v_add_f32_e32 v28, v28, v140
	ds_read_b32 v155, v36 offset:64
	s_waitcnt lgkmcnt(14)
	v_add_f32_e32 v29, v29, v141
	ds_read_b32 v60, v36 offset:44
	v_cndmask_b32_e32 v28, v240, v28, vcc
	v_cndmask_b32_e64 v29, v240, v29, s[16:17]
	v_cmp_lt_i32_e32 vcc, 17, v76
	v_cmp_lt_i32_e64 s[16:17], 18, v76
	s_waitcnt lgkmcnt(14)
	v_add_f32_e32 v30, v30, v142
	ds_read_b32 v61, v36 offset:40
	s_waitcnt lgkmcnt(14)
	v_add_f32_e32 v31, v31, v143
	ds_read_b32 v62, v36 offset:36
	v_cndmask_b32_e32 v30, v240, v30, vcc
	v_cndmask_b32_e64 v31, v240, v31, s[16:17]
	v_cmp_lt_i32_e32 vcc, 23, v76
	v_cmp_lt_i32_e64 s[16:17], 24, v76
	s_waitcnt lgkmcnt(14)
	v_add_f32_e32 v32, v32, v144
	ds_read_b32 v63, v36 offset:32
	s_waitcnt lgkmcnt(14)
	v_add_f32_e32 v33, v33, v145
	ds_read_b32 v64, v36 offset:12
	v_cndmask_b32_e32 v32, v240, v32, vcc
	v_cndmask_b32_e64 v33, v240, v33, s[16:17]
	v_cmp_lt_i32_e32 vcc, 25, v76
	v_cmp_lt_i32_e64 s[16:17], 26, v76
	s_waitcnt lgkmcnt(14)
	v_add_f32_e32 v34, v34, v146
	ds_read_b32 v65, v36 offset:8
	s_waitcnt lgkmcnt(14)
	v_add_f32_e32 v35, v35, v147
	ds_read_b32 v66, v36 offset:4
	v_cndmask_b32_e32 v34, v240, v34, vcc
	v_cndmask_b32_e64 v35, v240, v35, s[16:17]
	v_cmp_lt_i32_e32 vcc, 31, v76
	v_cmp_lt_i32_e64 s[16:17], 32, v76
	s_waitcnt lgkmcnt(14)
	v_add_f32_e32 v4, v4, v148
	ds_read_b32 v67, v36 offset:0
	s_waitcnt lgkmcnt(14)
	v_add_f32_e32 v5, v5, v149
	v_cndmask_b32_e32 v4, v240, v4, vcc
	v_cndmask_b32_e64 v5, v240, v5, s[16:17]
	v_cmp_lt_i32_e32 vcc, 33, v76
	v_cmp_lt_i32_e64 s[16:17], 34, v76
	s_waitcnt lgkmcnt(13)
	v_add_f32_e32 v6, v6, v150
	s_waitcnt lgkmcnt(12)
	v_add_f32_e32 v7, v7, v151
	v_cndmask_b32_e32 v6, v240, v6, vcc
	v_cndmask_b32_e64 v7, v240, v7, s[16:17]
	v_cmp_lt_i32_e32 vcc, 39, v76
	v_cmp_lt_i32_e64 s[16:17], 40, v76
	s_waitcnt lgkmcnt(11)
	v_add_f32_e32 v8, v8, v152
	s_waitcnt lgkmcnt(10)
	v_add_f32_e32 v9, v9, v153
	v_cndmask_b32_e32 v8, v240, v8, vcc
	v_cndmask_b32_e64 v9, v240, v9, s[16:17]
	v_cmp_lt_i32_e32 vcc, 41, v76
	v_cmp_lt_i32_e64 s[16:17], 42, v76
	s_waitcnt lgkmcnt(9)
	v_add_f32_e32 v10, v10, v154
	s_waitcnt lgkmcnt(8)
	v_add_f32_e32 v11, v11, v155
	v_cndmask_b32_e32 v10, v240, v10, vcc
	v_cndmask_b32_e64 v11, v240, v11, s[16:17]
	v_cmp_lt_i32_e32 vcc, 47, v76
	v_cmp_lt_i32_e64 s[16:17], 48, v76
	s_waitcnt lgkmcnt(7)
	v_add_f32_e32 v12, v12, v60
	s_waitcnt lgkmcnt(6)
	v_add_f32_e32 v13, v13, v61
	v_cndmask_b32_e32 v12, v240, v12, vcc
	v_cndmask_b32_e64 v13, v240, v13, s[16:17]
	v_cmp_lt_i32_e32 vcc, 49, v76
	v_cmp_lt_i32_e64 s[16:17], 50, v76
	s_waitcnt lgkmcnt(5)
	v_add_f32_e32 v14, v14, v62
	s_waitcnt lgkmcnt(4)
	v_add_f32_e32 v15, v15, v63
	v_cndmask_b32_e32 v14, v240, v14, vcc
	v_cndmask_b32_e64 v15, v240, v15, s[16:17]
	v_cmp_lt_i32_e32 vcc, 55, v76
	v_cmp_lt_i32_e64 s[16:17], 56, v76
	s_waitcnt lgkmcnt(3)
	v_add_f32_e32 v16, v16, v64
	s_waitcnt lgkmcnt(2)
	v_add_f32_e32 v17, v17, v65
	v_cndmask_b32_e32 v16, v240, v16, vcc
	v_cndmask_b32_e64 v17, v240, v17, s[16:17]
	v_cmp_lt_i32_e32 vcc, 57, v76
	v_cmp_lt_i32_e64 s[16:17], 58, v76
	s_waitcnt lgkmcnt(1)
	v_add_f32_e32 v18, v18, v66
	s_waitcnt lgkmcnt(0)
	v_add_f32_e32 v19, v19, v67
	v_cndmask_b32_e32 v18, v240, v18, vcc
	v_cndmask_b32_e64 v19, v240, v19, s[16:17]
